# dilcomb loads hoisted + phase-C unit balance thresholds k=5 (d=2 for g>=27, d=1 for 5<=g<27)
# speedup vs baseline: 1.0028x; 1.0028x over previous
; __global__ void __launch_bounds__(256, 2) hybrid_megakernel(Params p) {
;     ...
;       const int gi = vb >> 4;
;       int start = 0, mine = 0;
;       for (int g2 = 0; g2 <= gi; ++g2) {
;         const int n = 32 - g2;
;         const int d = (n <= 10) ? 2 : (n <= 22) ? 1 : 0;
;         if (g2 < gi) start += 2 * d; else mine = d;
;       }
;       start += ((vb >> 3) & 1) * mine;
.LBB0_407:
	s_cmp_gt_u32 s2, 4
	s_cselect_b64 s[4:5], -1, 0
	s_cmp_lt_u32 s2, 27
	v_cndmask_b32_e64 v1, 0, 1, s[4:5]
	s_cselect_b64 vcc, -1, 0
	v_cndmask_b32_e32 v1, 2, v1, vcc
	s_cmp_lt_i32 s2, s0
	v_lshlrev_b32_e32 v2, 1, v1
	s_cselect_b64 vcc, -1, 0
	s_add_i32 s2, s2, 1
	v_cndmask_b32_e32 v2, 0, v2, vcc
	v_cndmask_b32_e32 v116, v1, v116, vcc
	s_cmp_eq_u32 s1, s2
	v_add_u32_e32 v0, v2, v0
	s_cbranch_scc0 .LBB0_407
	v_cmp_gt_i32_e32 vcc, 1, v116
	s_cbranch_vccz .LBB0_410
	s_branch .LBB0_345
